# v36 + attention QK: K-fragment LDS reads issued up to 14 fragments ahead of their MFMAs (hi fragments in separate registers) instead of one ahead
# baseline (speedup 1.0000x reference)
; __device__ __forceinline__ AttnGeom attn_geom(int it) {
;     AttnGeom G; G.hd = it / 192; const int qt = it % 192;
;     int T, lt; if (qt < 64) { G.seq_start = (qt >> 4) * 2048; T = 2048; lt = qt & 15; } else { G.seq_start = 8192; T = 16384; lt = qt - 64; }
;     const int g = G.hd >> 3; G.dil = g == 0 ? 1 : (g == 1 ? 4 : 16); G.n_lat = T / G.dil; const int tpr = G.n_lat >> 7; G.r = lt / tpr; G.q0 = (lt % tpr) << 7; return G;
; __device__ void attn_items(const Params& p, unsigned char* shm) {
;     ...
;         f32x4 s[9];
; #pragma unroll
;         for (int kt = 0; kt < 9; ++kt) { const bf16_t* kr = Ks + (16 * w + 16 * kt + fr) * 72 + fq * 8;
;             f32x4 a = (f32x4){0.f, 0.f, 0.f, 0.f};
;             a = __builtin_amdgcn_mfma_f32_16x16x32_bf16(aq0, *(const bf16x8*)kr, a, 0, 0, 0);
;             a = __builtin_amdgcn_mfma_f32_16x16x32_bf16(aq1, *(const bf16x8*)(kr + 32), a, 0, 0, 0); s[kt] = a; }
;         float mx[4], ls[4];
; #pragma unroll
;         for (int i = 0; i < 4; ++i) { const int qi = fq * 4 + i; float m = -3.0e38f;
; #pragma unroll
;             for (int kt = 0; kt < 9; ++kt) { const int rel = 16 * kt + fr - 64 - qi, klat = G.q0 - 64 + 16 * w + 16 * kt + fr;
;                 const bool ok = rel >= -64 && rel <= 64 && klat >= 0 && klat < G.n_lat; const int bi = min(max(rel + 64, 0), 128);
;                 const float v = ok ? s[kt][i] + bs[bi] : -1.0e30f; s[kt][i] = v; m = fmaxf(m, v); }
.LBB0_373:
	v_add_u32_e32 v0, v101, v114
	ds_read_b128 v[60:63], v0
	ds_read_b128 v[184:187], v0 offset:64
	ds_read_b128 v[64:67], v164
	ds_read_b128 v[188:191], v164 offset:64
	ds_read_b128 v[68:71], v165
	ds_read_b128 v[196:199], v165 offset:64
	ds_read_b128 v[72:75], v166
	ds_read_b128 v[200:203], v166 offset:64
	ds_read_b128 v[76:79], v167
	ds_read_b128 v[204:207], v167 offset:64
	ds_read_b128 v[80:83], v168
	ds_read_b128 v[208:211], v168 offset:64
	ds_read_b128 v[84:87], v169
	ds_read_b128 v[212:215], v169 offset:64
	s_mul_hi_i32 s0, s4, 0x2aaaaaab
	s_lshr_b32 s1, s0, 31
	s_ashr_i32 s0, s0, 5
	s_add_i32 s58, s0, s1
	s_mul_i32 s0, s58, 0xffffff40
	s_add_i32 s0, s4, s0
	s_and_b32 s4, s0, 15
	s_sub_i32 s5, s0, 64
	s_cmp_lt_i32 s0, 64
	s_cselect_b64 s[60:61], -1, 0
	s_and_b64 s[0:1], s[60:61], exec
	s_movk_i32 s0, 0x800
	s_cselect_b32 s6, s4, s5
	s_cselect_b32 s0, s0, 0x4000
	s_and_b32 s1, s58, -8
	s_cmp_eq_u32 s1, 8
	s_cselect_b32 s1, 2, 4
	s_cmp_gt_u32 s58, 7
	s_cselect_b32 s4, s1, 0
	s_lshr_b32 s8, s0, s4
	s_lshr_b32 s0, s8, 7
	s_add_i32 s0, s0, -1
	s_and_b32 s0, s0, s6
	s_lshl_b32 s5, s0, 7
	s_mul_i32 s0, s58, 0x210
	s_add_i32 s7, s0, 0
	v_add_u32_e32 v2, s5, v102
	v_readlane_b32 s0, v254, 49
	v_or_b32_e32 v0, v2, v93
	v_cmp_lt_i32_e32 vcc, -1, v2
	v_readlane_b32 s1, v254, 50
	s_add_i32 s7, s7, 0x1d800
	s_and_b64 s[0:1], s[0:1], vcc
	v_cmp_gt_i32_e64 s[74:75], s8, v0
	s_and_b64 s[18:19], s[0:1], s[74:75]
	v_mov_b32_e32 v3, 0xf149f2ca
	s_waitcnt lgkmcnt(13)
	v_mfma_f32_16x16x32_bf16 v[60:63], v[56:59], v[60:63], 0
	s_waitcnt lgkmcnt(12)
	v_mfma_f32_16x16x32_bf16 v[60:63], v[52:55], v[184:187], v[60:63]
	ds_read_b128 v[88:91], v170
	ds_read_b128 v[216:219], v170 offset:64
	s_waitcnt lgkmcnt(13)
	v_mfma_f32_16x16x32_bf16 v[64:67], v[56:59], v[64:67], 0
	s_waitcnt lgkmcnt(12)
	v_mfma_f32_16x16x32_bf16 v[64:67], v[52:55], v[188:191], v[64:67]
	ds_read_b128 v[176:179], v171
	ds_read_b128 v[184:187], v171 offset:64
	s_waitcnt lgkmcnt(13)
	v_mfma_f32_16x16x32_bf16 v[68:71], v[56:59], v[68:71], 0
	s_waitcnt lgkmcnt(12)
	v_mfma_f32_16x16x32_bf16 v[68:71], v[52:55], v[196:199], v[68:71]
	s_waitcnt lgkmcnt(11)
	v_mfma_f32_16x16x32_bf16 v[72:75], v[56:59], v[72:75], 0
	s_waitcnt lgkmcnt(10)
	v_mfma_f32_16x16x32_bf16 v[72:75], v[52:55], v[200:203], v[72:75]
	s_waitcnt lgkmcnt(9)
	v_mfma_f32_16x16x32_bf16 v[76:79], v[56:59], v[76:79], 0
	s_waitcnt lgkmcnt(8)
	v_mfma_f32_16x16x32_bf16 v[76:79], v[52:55], v[204:207], v[76:79]
	s_waitcnt lgkmcnt(7)
	v_mfma_f32_16x16x32_bf16 v[80:83], v[56:59], v[80:83], 0
	s_waitcnt lgkmcnt(6)
	v_mfma_f32_16x16x32_bf16 v[80:83], v[52:55], v[208:211], v[80:83]
	s_waitcnt lgkmcnt(5)
	v_mfma_f32_16x16x32_bf16 v[84:87], v[56:59], v[84:87], 0
	s_waitcnt lgkmcnt(4)
	v_mfma_f32_16x16x32_bf16 v[84:87], v[52:55], v[212:215], v[84:87]
	s_waitcnt lgkmcnt(3)
	v_mfma_f32_16x16x32_bf16 v[88:91], v[56:59], v[88:91], 0
	s_waitcnt lgkmcnt(2)
	v_mfma_f32_16x16x32_bf16 v[88:91], v[52:55], v[216:219], v[88:91]
	s_waitcnt lgkmcnt(1)
	v_mfma_f32_16x16x32_bf16 v[56:59], v[56:59], v[176:179], 0
	s_waitcnt lgkmcnt(0)
	v_mfma_f32_16x16x32_bf16 v[52:55], v[52:55], v[184:187], v[56:59]
	s_nop 3
	v_lshl_add_u32 v57, v115, 2, s7
	ds_read_b32 v184, v57
	ds_read_b32 v185, v57 offset:64
	ds_read_b32 v186, v57 offset:128
	ds_read_b32 v187, v57 offset:192
	ds_read_b32 v188, v57 offset:256
	ds_read_b32 v189, v57 offset:320
	ds_read_b32 v190, v57 offset:384
	ds_read_b32 v191, v57 offset:448
	ds_read_b32 v192, v57 offset:512
	v_lshl_add_u32 v232, v116, 2, s7
	ds_read_b32 v193, v232
	ds_read_b32 v194, v232 offset:64
	ds_read_b32 v196, v232 offset:128
	ds_read_b32 v197, v232 offset:192
	ds_read_b32 v198, v232 offset:256
	ds_read_b32 v199, v232 offset:320
	ds_read_b32 v200, v232 offset:384
	ds_read_b32 v201, v232 offset:448
	ds_read_b32 v202, v232 offset:512
	v_lshl_add_u32 v233, v118, 2, s7
	ds_read_b32 v203, v233
	ds_read_b32 v204, v233 offset:64
	ds_read_b32 v205, v233 offset:128
	ds_read_b32 v206, v233 offset:192
	ds_read_b32 v207, v233 offset:256
	ds_read_b32 v208, v233 offset:320
	ds_read_b32 v209, v233 offset:384
	ds_read_b32 v210, v233 offset:448
	ds_read_b32 v211, v233 offset:512
	v_lshl_add_u32 v232, v120, 2, s7
	ds_read_b32 v212, v232
	ds_read_b32 v213, v232 offset:64
	ds_read_b32 v214, v232 offset:128
	ds_read_b32 v215, v232 offset:192
	ds_read_b32 v216, v232 offset:256
	ds_read_b32 v217, v232 offset:320
	ds_read_b32 v218, v232 offset:384
	ds_read_b32 v219, v232 offset:448
	ds_read_b32 v220, v232 offset:512
	v_mov_b32_e32 v56, 0xf149f2ca
	s_waitcnt lgkmcnt(0)
; __device__ void attn_items(const Params& p, unsigned char* shm) {
;     ...
;         for (int i = 0; i < 4; ++i) { const int qi = fq * 4 + i; float m = -3.0e38f;
; #pragma unroll
;             for (int kt = 0; kt < 9; ++kt) { const int rel = 16 * kt + fr - 64 - qi, klat = G.q0 - 64 + 16 * w + 16 * kt + fr;
;                 const bool ok = rel >= -64 && rel <= 64 && klat >= 0 && klat < G.n_lat; const int bi = min(max(rel + 64, 0), 128);
;                 const float v = ok ? s[kt][i] + bs[bi] : -1.0e30f; s[kt][i] = v; m = fmaxf(m, v); }
;             m = fmaxf(m, __shfl_xor(m, 1)); m = fmaxf(m, __shfl_xor(m, 2)); m = fmaxf(m, __shfl_xor(m, 4)); m = fmaxf(m, __shfl_xor(m, 8));
;             float sum = 0.f;
; #pragma unroll
;             for (int kt = 0; kt < 9; ++kt) { const float pv = __expf(s[kt][i] - m); s[kt][i] = pv; sum += pv; }
;             sum += __shfl_xor(sum, 1); sum += __shfl_xor(sum, 2); sum += __shfl_xor(sum, 4); sum += __shfl_xor(sum, 8);
;             mx[i] = m; ls[i] = sum; }
	v_add_f32_e32 v184, v60, v184
	v_cndmask_b32_e64 v56, v56, v184, s[18:19]
	v_add_u32_e32 v0, v2, v127
	s_movk_i32 s0, 0xffef
	v_cmp_lt_i32_e64 s[76:77], s0, v2
	v_cmp_gt_i32_e64 s[78:79], s8, v0
	s_and_b64 s[62:63], s[76:77], s[78:79]
	v_add_f32_e32 v185, v64, v185
	v_cndmask_b32_e64 v3, v3, v185, s[62:63]
	v_add_u32_e32 v0, v2, v129
	s_movk_i32 s0, 0xffdf
	v_cmp_lt_i32_e64 s[76:77], s0, v2
	v_cmp_gt_i32_e64 s[78:79], s8, v0
	s_and_b64 s[64:65], s[76:77], s[78:79]
	v_mov_b32_e32 v58, 0xf149f2ca
	v_mov_b32_e32 v59, 0xf149f2ca
	v_add_f32_e32 v186, v68, v186
	v_cndmask_b32_e64 v59, v59, v186, s[64:65]
	v_add_u32_e32 v0, v2, v132
	s_movk_i32 s0, 0xffcf
	v_cmp_lt_i32_e64 s[76:77], s0, v2
	v_cmp_gt_i32_e64 s[78:79], s8, v0
	s_and_b64 s[66:67], s[76:77], s[78:79]
	v_add_f32_e32 v187, v72, v187
	v_cndmask_b32_e64 v58, v58, v187, s[66:67]
	v_add_u32_e32 v0, s5, v99
	v_or_b32_e32 v60, v0, v93
	v_cmp_lt_i32_e64 s[76:77], -1, v0
	v_cmp_gt_i32_e64 s[78:79], s8, v60
	s_and_b64 s[68:69], s[76:77], s[78:79]
	v_mov_b32_e32 v60, 0xf149f2ca
	v_mov_b32_e32 v64, 0xf149f2ca
	v_add_f32_e32 v188, v76, v188
	v_cndmask_b32_e64 v64, v64, v188, s[68:69]
	v_add_u32_e32 v68, v2, v150
	s_movk_i32 s0, 0xffaf
	v_cmp_lt_i32_e64 s[76:77], s0, v2
	v_cmp_gt_i32_e64 s[78:79], s8, v68
	s_and_b64 s[70:71], s[76:77], s[78:79]
	v_add_f32_e32 v189, v80, v189
	v_cndmask_b32_e64 v60, v60, v189, s[70:71]
	v_add_u32_e32 v68, v2, v151
	s_movk_i32 s0, 0xff9f
	v_cmp_lt_i32_e64 s[76:77], s0, v2
	v_cmp_gt_i32_e64 s[78:79], s8, v68
	s_and_b64 s[72:73], s[76:77], s[78:79]
	v_mov_b32_e32 v72, 0xf149f2ca
	v_mov_b32_e32 v76, 0xf149f2ca
	v_add_f32_e32 v190, v84, v190
	v_cndmask_b32_e64 v76, v76, v190, s[72:73]
	v_add_u32_e32 v68, v2, v152
	s_movk_i32 s0, 0xff8f
	v_cmp_lt_i32_e64 s[76:77], s0, v2
	v_cmp_gt_i32_e64 s[78:79], s8, v68
	s_and_b64 s[38:39], s[76:77], s[78:79]
	v_add_f32_e32 v191, v88, v191
	v_cndmask_b32_e64 v72, v72, v191, s[38:39]
	v_readlane_b32 s0, v254, 37
	v_add_u32_e32 v68, v2, v153
	v_cmp_lt_i32_e64 s[76:77], s23, v2
	v_readlane_b32 s1, v254, 38
	s_and_b64 s[0:1], s[0:1], s[76:77]
	v_cmp_gt_i32_e64 s[78:79], s8, v68
	s_and_b64 s[8:9], s[0:1], s[78:79]
	v_mov_b32_e32 v68, 0xf149f2ca
	v_mov_b32_e32 v84, 0xf149f2ca
	v_add_f32_e32 v192, v52, v192
	v_cndmask_b32_e64 v84, v84, v192, s[8:9]
	v_max_f32_e32 v2, v56, v56
	v_max_f32_e32 v2, 0xff61b1e6, v2
	v_max3_f32 v2, v2, v3, v59
	v_max3_f32 v2, v2, v58, v64
	v_max3_f32 v2, v2, v60, v76
	v_max3_f32 v2, v2, v72, v84
	s_nop 1
	v_mov_b32_dpp v52, v2 quad_perm:[1,0,3,2] row_mask:0xf bank_mask:0xf
	v_readlane_b32 s0, v255, 0
	v_readlane_b32 s1, v255, 1
	s_and_b64 s[0:1], s[0:1], vcc
	s_and_b64 s[8:9], s[0:1], s[74:75]
	s_waitcnt lgkmcnt(0)
	v_max_f32_e32 v52, v52, v52
	v_max_f32_e32 v2, v2, v52
	s_nop 1
	v_mov_b32_dpp v52, v2 quad_perm:[2,3,0,1] row_mask:0xf bank_mask:0xf
	s_waitcnt lgkmcnt(0)
	v_max_f32_e32 v52, v52, v52
	v_max_f32_e32 v2, v2, v52
	s_nop 1
	v_mov_b32_dpp v52, v2 row_shl:4 row_mask:0xf bank_mask:0x5
	v_mov_b32_dpp v52, v2 row_shr:4 row_mask:0xf bank_mask:0xa
	s_waitcnt lgkmcnt(0)
	v_max_f32_e32 v52, v52, v52
	v_max_f32_e32 v2, v2, v52
	s_nop 1
	v_mov_b32_dpp v52, v2 row_shl:8 row_mask:0xf bank_mask:0x3
	v_mov_b32_dpp v52, v2 row_shr:8 row_mask:0xf bank_mask:0xc
	s_waitcnt lgkmcnt(0)
	v_max_f32_e32 v52, v52, v52
	v_max_f32_e32 v2, v2, v52
	v_sub_f32_e32 v52, v56, v2
	v_sub_f32_e32 v3, v3, v2
	v_mul_f32_e32 v52, 0x3fb8aa3b, v52
	v_sub_f32_e32 v56, v59, v2
	v_mul_f32_e32 v3, 0x3fb8aa3b, v3
	v_exp_f32_e32 v80, v52
	v_sub_f32_e32 v57, v58, v2
	v_sub_f32_e32 v59, v60, v2
	v_sub_f32_e32 v60, v76, v2
	v_mul_f32_e32 v56, 0x3fb8aa3b, v56
	v_exp_f32_e32 v76, v3
	v_sub_f32_e32 v58, v64, v2
	v_mul_f32_e32 v57, 0x3fb8aa3b, v57
	v_exp_f32_e32 v64, v56
	v_mul_f32_e32 v58, 0x3fb8aa3b, v58
	v_mul_f32_e32 v88, 0x3fb8aa3b, v60
	v_exp_f32_e32 v60, v57
	v_mul_f32_e32 v59, 0x3fb8aa3b, v59
	v_exp_f32_e32 v57, v58
	v_add_f32_e32 v3, 0, v80
	v_sub_f32_e32 v72, v72, v2
	v_exp_f32_e32 v56, v59
	v_add_f32_e32 v3, v76, v3
	v_exp_f32_e32 v52, v88
	v_add_f32_e32 v3, v64, v3
	v_mul_f32_e32 v58, 0x3fb8aa3b, v72
	v_sub_f32_e32 v59, v84, v2
	v_add_f32_e32 v3, v60, v3
	v_exp_f32_e32 v58, v58
	v_mul_f32_e32 v59, 0x3fb8aa3b, v59
	v_add_f32_e32 v3, v57, v3
	v_exp_f32_e32 v59, v59
	v_add_f32_e32 v3, v56, v3
	v_add_f32_e32 v3, v52, v3
	v_add_f32_e32 v3, v58, v3
	v_add_f32_e32 v3, v59, v3
	s_nop 1
	v_mov_b32_dpp v72, v3 quad_perm:[1,0,3,2] row_mask:0xf bank_mask:0xf
	s_waitcnt lgkmcnt(0)
	v_add_f32_e32 v3, v3, v72
	s_nop 1
	v_mov_b32_dpp v72, v3 quad_perm:[2,3,0,1] row_mask:0xf bank_mask:0xf
	s_waitcnt lgkmcnt(0)
	v_add_f32_e32 v3, v3, v72
	s_nop 1
	v_mov_b32_dpp v72, v3 row_shl:4 row_mask:0xf bank_mask:0x5
	v_mov_b32_dpp v72, v3 row_shr:4 row_mask:0xf bank_mask:0xa
	s_waitcnt lgkmcnt(0)
	v_add_f32_e32 v176, v3, v72
	s_nop 1
	v_mov_b32_dpp v177, v176 row_shl:8 row_mask:0xf bank_mask:0x3
	v_mov_b32_dpp v177, v176 row_shr:8 row_mask:0xf bank_mask:0xc
	v_lshl_add_u32 v3, v116, 2, s7
	v_add_f32_e32 v193, v61, v193
	v_cndmask_b32_e64 v68, v68, v193, s[8:9]
	v_mov_b32_e32 v61, 0xf149f2ca
	v_mov_b32_e32 v72, 0xf149f2ca
	v_add_f32_e32 v194, v65, v194
	v_cndmask_b32_e64 v72, v72, v194, s[62:63]
	v_add_f32_e32 v196, v69, v196
	v_cndmask_b32_e64 v61, v61, v196, s[64:65]
	v_mov_b32_e32 v65, 0xf149f2ca
	v_mov_b32_e32 v69, 0xf149f2ca
	v_add_f32_e32 v197, v73, v197
	v_cndmask_b32_e64 v69, v69, v197, s[66:67]
	v_add_f32_e32 v198, v77, v198
	v_cndmask_b32_e64 v65, v65, v198, s[68:69]
	v_mov_b32_e32 v73, 0xf149f2ca
	v_mov_b32_e32 v84, 0xf149f2ca
	v_add_f32_e32 v199, v81, v199
	v_cndmask_b32_e64 v84, v84, v199, s[70:71]
	v_add_f32_e32 v200, v85, v200
	v_cndmask_b32_e64 v73, v73, v200, s[72:73]
	v_mov_b32_e32 v77, 0xf149f2ca
	v_mov_b32_e32 v81, 0xf149f2ca
	v_add_f32_e32 v201, v89, v201
	v_cndmask_b32_e64 v81, v81, v201, s[38:39]
	v_readlane_b32 s0, v255, 2
	v_readlane_b32 s1, v255, 3
	s_and_b64 s[0:1], s[0:1], s[76:77]
	s_and_b64 s[8:9], s[0:1], s[78:79]
	v_add_f32_e32 v202, v53, v202
	v_cndmask_b32_e64 v77, v77, v202, s[8:9]
	v_max_f32_e32 v3, v68, v68
	v_max_f32_e32 v3, 0xff61b1e6, v3
	v_max3_f32 v3, v3, v72, v61
	v_max3_f32 v3, v3, v69, v65
	v_max3_f32 v3, v3, v84, v73
	v_max3_f32 v3, v3, v81, v77
	s_nop 1
	v_mov_b32_dpp v53, v3 quad_perm:[1,0,3,2] row_mask:0xf bank_mask:0xf
	v_readlane_b32 s0, v255, 4
	v_readlane_b32 s1, v255, 5
	s_and_b64 s[0:1], s[0:1], vcc
	s_and_b64 s[8:9], s[0:1], s[74:75]
	s_waitcnt lgkmcnt(0)
; __device__ void attn_items(const Params& p, unsigned char* shm) {
;     ...
;         for (int i = 0; i < 4; ++i) { const int qi = fq * 4 + i; float m = -3.0e38f;
; #pragma unroll
;             for (int kt = 0; kt < 9; ++kt) { const int rel = 16 * kt + fr - 64 - qi, klat = G.q0 - 64 + 16 * w + 16 * kt + fr;
;                 const bool ok = rel >= -64 && rel <= 64 && klat >= 0 && klat < G.n_lat; const int bi = min(max(rel + 64, 0), 128);
;                 const float v = ok ? s[kt][i] + bs[bi] : -1.0e30f; s[kt][i] = v; m = fmaxf(m, v); }
;             m = fmaxf(m, __shfl_xor(m, 1)); m = fmaxf(m, __shfl_xor(m, 2)); m = fmaxf(m, __shfl_xor(m, 4)); m = fmaxf(m, __shfl_xor(m, 8));
;             float sum = 0.f;
; #pragma unroll
;             for (int kt = 0; kt < 9; ++kt) { const float pv = __expf(s[kt][i] - m); s[kt][i] = pv; sum += pv; }
;             sum += __shfl_xor(sum, 1); sum += __shfl_xor(sum, 2); sum += __shfl_xor(sum, 4); sum += __shfl_xor(sum, 8);
;             mx[i] = m; ls[i] = sum; }
	v_max_f32_e32 v53, v53, v53
	v_max_f32_e32 v3, v3, v53
	s_nop 1
	v_mov_b32_dpp v53, v3 quad_perm:[2,3,0,1] row_mask:0xf bank_mask:0xf
	s_waitcnt lgkmcnt(0)
	v_max_f32_e32 v53, v53, v53
	v_max_f32_e32 v3, v3, v53
	s_nop 1
	v_mov_b32_dpp v53, v3 row_shl:4 row_mask:0xf bank_mask:0x5
	v_mov_b32_dpp v53, v3 row_shr:4 row_mask:0xf bank_mask:0xa
	s_waitcnt lgkmcnt(0)
	v_max_f32_e32 v53, v53, v53
	v_max_f32_e32 v3, v3, v53
	s_nop 1
	v_mov_b32_dpp v53, v3 row_shl:8 row_mask:0xf bank_mask:0x3
	v_mov_b32_dpp v53, v3 row_shr:8 row_mask:0xf bank_mask:0xc
	s_waitcnt lgkmcnt(0)
	v_max_f32_e32 v53, v53, v53
	v_max_f32_e32 v3, v3, v53
	v_sub_f32_e32 v53, v68, v3
	v_sub_f32_e32 v68, v72, v3
	v_mul_f32_e32 v53, 0x3fb8aa3b, v53
	v_sub_f32_e32 v61, v61, v3
	v_mul_f32_e32 v68, 0x3fb8aa3b, v68
	v_exp_f32_e32 v97, v53
	v_sub_f32_e32 v69, v69, v3
	v_mul_f32_e32 v61, 0x3fb8aa3b, v61
	v_exp_f32_e32 v89, v68
	v_sub_f32_e32 v65, v65, v3
	v_mul_f32_e32 v69, 0x3fb8aa3b, v69
	v_exp_f32_e32 v88, v61
	v_sub_f32_e32 v72, v84, v3
	v_mul_f32_e32 v65, 0x3fb8aa3b, v65
	v_exp_f32_e32 v85, v69
	v_sub_f32_e32 v73, v73, v3
	v_sub_f32_e32 v81, v81, v3
	v_mul_f32_e32 v72, 0x3fb8aa3b, v72
	v_exp_f32_e32 v65, v65
	v_add_f32_e32 v68, 0, v97
	v_mul_f32_e32 v73, 0x3fb8aa3b, v73
	v_exp_f32_e32 v61, v72
	v_add_f32_e32 v68, v89, v68
	v_mul_f32_e32 v69, 0x3fb8aa3b, v81
	v_exp_f32_e32 v53, v73
	v_add_f32_e32 v68, v88, v68
	v_exp_f32_e32 v81, v69
	v_sub_f32_e32 v69, v77, v3
	v_add_f32_e32 v68, v85, v68
	v_mul_f32_e32 v69, 0x3fb8aa3b, v69
	v_add_f32_e32 v68, v65, v68
	v_exp_f32_e32 v84, v69
	v_add_f32_e32 v68, v61, v68
	v_add_f32_e32 v68, v53, v68
	v_add_f32_e32 v68, v81, v68
	v_add_f32_e32 v68, v84, v68
	s_nop 1
	v_mov_b32_dpp v69, v68 quad_perm:[1,0,3,2] row_mask:0xf bank_mask:0xf
	v_mov_b32_e32 v72, 0xf149f2ca
	v_lshl_add_u32 v77, v118, 2, s7
	v_mov_b32_e32 v73, 0xf149f2ca
	s_waitcnt lgkmcnt(0)
	v_add_f32_e32 v68, v68, v69
	s_nop 1
	v_mov_b32_dpp v69, v68 quad_perm:[2,3,0,1] row_mask:0xf bank_mask:0xf
	s_waitcnt lgkmcnt(0)
	v_add_f32_e32 v68, v68, v69
	s_nop 1
	v_mov_b32_dpp v69, v68 row_shl:4 row_mask:0xf bank_mask:0x5
	v_mov_b32_dpp v69, v68 row_shr:4 row_mask:0xf bank_mask:0xa
	s_waitcnt lgkmcnt(0)
	v_add_f32_e32 v68, v68, v69
	s_nop 1
	v_mov_b32_dpp v69, v68 row_shl:8 row_mask:0xf bank_mask:0x3
	v_mov_b32_dpp v69, v68 row_shr:8 row_mask:0xf bank_mask:0xc
	v_add_f32_e32 v203, v62, v203
	v_cndmask_b32_e64 v73, v73, v203, s[8:9]
	v_add_f32_e32 v204, v66, v204
	v_cndmask_b32_e64 v72, v72, v204, s[62:63]
	v_mov_b32_e32 v62, 0xf149f2ca
	v_mov_b32_e32 v66, 0xf149f2ca
	v_add_f32_e32 v205, v70, v205
	v_cndmask_b32_e64 v66, v66, v205, s[64:65]
	v_add_f32_e32 v206, v74, v206
	v_cndmask_b32_e64 v62, v62, v206, s[66:67]
	v_mov_b32_e32 v74, 0xf149f2ca
	v_mov_b32_e32 v178, 0xf149f2ca
	v_add_f32_e32 v207, v78, v207
	v_cndmask_b32_e64 v178, v178, v207, s[68:69]
	v_add_f32_e32 v208, v82, v208
	v_cndmask_b32_e64 v74, v74, v208, s[70:71]
	v_mov_b32_e32 v78, 0xf149f2ca
	v_mov_b32_e32 v82, 0xf149f2ca
	v_add_f32_e32 v209, v86, v209
	v_cndmask_b32_e64 v82, v82, v209, s[72:73]
	v_add_f32_e32 v210, v90, v210
	v_cndmask_b32_e64 v78, v78, v210, s[38:39]
	v_readlane_b32 s0, v255, 6
	v_readlane_b32 s1, v255, 7
	s_and_b64 s[0:1], s[0:1], s[76:77]
	s_and_b64 s[8:9], s[0:1], s[78:79]
	v_mov_b32_e32 v77, 0xf149f2ca
	v_mov_b32_e32 v180, 0xf149f2ca
	v_add_f32_e32 v211, v54, v211
	v_cndmask_b32_e64 v180, v180, v211, s[8:9]
	v_max_f32_e32 v54, v73, v73
	v_max_f32_e32 v54, 0xff61b1e6, v54
	v_max3_f32 v54, v54, v72, v66
	v_max3_f32 v54, v54, v62, v178
	v_max3_f32 v54, v54, v74, v82
	v_max3_f32 v54, v54, v78, v180
	s_nop 1
	v_mov_b32_dpp v70, v54 quad_perm:[1,0,3,2] row_mask:0xf bank_mask:0xf
	v_readlane_b32 s0, v255, 12
	v_readlane_b32 s1, v255, 13
	s_and_b64 s[0:1], s[0:1], vcc
	s_and_b64 s[8:9], s[0:1], s[74:75]
	s_waitcnt lgkmcnt(0)
	v_max_f32_e32 v70, v70, v70
	v_max_f32_e32 v54, v54, v70
	s_nop 1
	v_mov_b32_dpp v70, v54 quad_perm:[2,3,0,1] row_mask:0xf bank_mask:0xf
	s_waitcnt lgkmcnt(0)
	v_max_f32_e32 v70, v70, v70
	v_max_f32_e32 v54, v54, v70
	s_nop 1
	v_mov_b32_dpp v70, v54 row_shl:4 row_mask:0xf bank_mask:0x5
	v_mov_b32_dpp v70, v54 row_shr:4 row_mask:0xf bank_mask:0xa
	s_waitcnt lgkmcnt(0)
	v_max_f32_e32 v70, v70, v70
	v_max_f32_e32 v54, v54, v70
	s_nop 1
	v_mov_b32_dpp v70, v54 row_shl:8 row_mask:0xf bank_mask:0x3
	v_mov_b32_dpp v70, v54 row_shr:8 row_mask:0xf bank_mask:0xc
	s_waitcnt lgkmcnt(0)
	v_max_f32_e32 v70, v70, v70
	v_max_f32_e32 v70, v54, v70
	v_sub_f32_e32 v54, v73, v70
	v_sub_f32_e32 v72, v72, v70
	v_mul_f32_e32 v54, 0x3fb8aa3b, v54
	v_sub_f32_e32 v66, v66, v70
	v_mul_f32_e32 v72, 0x3fb8aa3b, v72
	v_exp_f32_e32 v179, v54
	v_sub_f32_e32 v62, v62, v70
	v_sub_f32_e32 v73, v178, v70
	v_mul_f32_e32 v66, 0x3fb8aa3b, v66
	v_exp_f32_e32 v178, v72
	v_mul_f32_e32 v62, 0x3fb8aa3b, v62
	v_exp_f32_e32 v90, v66
	v_sub_f32_e32 v74, v74, v70
	v_mul_f32_e32 v73, 0x3fb8aa3b, v73
	v_exp_f32_e32 v86, v62
	v_sub_f32_e32 v82, v82, v70
	v_sub_f32_e32 v78, v78, v70
	v_mul_f32_e32 v74, 0x3fb8aa3b, v74
	v_exp_f32_e32 v66, v73
	v_add_f32_e32 v72, 0, v179
	v_mul_f32_e32 v82, 0x3fb8aa3b, v82
	v_exp_f32_e32 v62, v74
	v_add_f32_e32 v72, v178, v72
	v_mul_f32_e32 v73, 0x3fb8aa3b, v78
	v_exp_f32_e32 v54, v82
	v_add_f32_e32 v72, v90, v72
	v_exp_f32_e32 v78, v73
	v_sub_f32_e32 v73, v180, v70
	v_add_f32_e32 v72, v86, v72
	v_mul_f32_e32 v73, 0x3fb8aa3b, v73
	v_add_f32_e32 v72, v66, v72
	v_exp_f32_e32 v82, v73
	v_add_f32_e32 v72, v62, v72
	v_add_f32_e32 v72, v54, v72
	v_add_f32_e32 v72, v78, v72
	v_add_f32_e32 v72, v82, v72
	s_nop 1
	v_mov_b32_dpp v73, v72 quad_perm:[1,0,3,2] row_mask:0xf bank_mask:0xf
	v_lshl_add_u32 v74, v120, 2, s7
	s_waitcnt lgkmcnt(0)
; __device__ __forceinline__ bf16_t f2bf(float f) { return (bf16_t)(cvt_pk_bf16(f, 0.f) & 0xffffu); }
; __device__ void attn_items(const Params& p, unsigned char* shm) {
;     ...
;         for (int i = 0; i < 4; ++i) { const int qi = fq * 4 + i; float m = -3.0e38f;
; #pragma unroll
;             for (int kt = 0; kt < 9; ++kt) { const int rel = 16 * kt + fr - 64 - qi, klat = G.q0 - 64 + 16 * w + 16 * kt + fr;
;                 const bool ok = rel >= -64 && rel <= 64 && klat >= 0 && klat < G.n_lat; const int bi = min(max(rel + 64, 0), 128);
;                 const float v = ok ? s[kt][i] + bs[bi] : -1.0e30f; s[kt][i] = v; m = fmaxf(m, v); }
;             m = fmaxf(m, __shfl_xor(m, 1)); m = fmaxf(m, __shfl_xor(m, 2)); m = fmaxf(m, __shfl_xor(m, 4)); m = fmaxf(m, __shfl_xor(m, 8));
;             float sum = 0.f;
; #pragma unroll
;             for (int kt = 0; kt < 9; ++kt) { const float pv = __expf(s[kt][i] - m); s[kt][i] = pv; sum += pv; }
;             sum += __shfl_xor(sum, 1); sum += __shfl_xor(sum, 2); sum += __shfl_xor(sum, 4); sum += __shfl_xor(sum, 8);
;             mx[i] = m; ls[i] = sum; }
;         bf16_t* Pw = Ps + w * 16 * 168;
; #pragma unroll
;         for (int i = 0; i < 4; ++i) {
; #pragma unroll
;             for (int kt = 0; kt < 9; ++kt) Pw[(fq * 4 + i) * 168 + 16 * kt + fr] = f2bf(s[kt][i]);
;             Pw[(fq * 4 + i) * 168 + 144 + fr] = 0; }
;         __syncthreads();
	v_add_f32_e32 v72, v72, v73
	s_nop 1
	v_mov_b32_dpp v73, v72 quad_perm:[2,3,0,1] row_mask:0xf bank_mask:0xf
	s_waitcnt lgkmcnt(0)
	v_add_f32_e32 v72, v72, v73
	s_nop 1
	v_mov_b32_dpp v73, v72 row_shl:4 row_mask:0xf bank_mask:0x5
	v_mov_b32_dpp v73, v72 row_shr:4 row_mask:0xf bank_mask:0xa
	s_waitcnt lgkmcnt(0)
	v_add_f32_e32 v72, v72, v73
	s_nop 1
	v_mov_b32_dpp v73, v72 row_shl:8 row_mask:0xf bank_mask:0x3
	v_mov_b32_dpp v73, v72 row_shr:8 row_mask:0xf bank_mask:0xc
	v_add_f32_e32 v212, v63, v212
	v_cndmask_b32_e64 v77, v77, v212, s[8:9]
	v_mov_b32_e32 v181, 0xf149f2ca
	v_mov_b32_e32 v183, 0xf149f2ca
	v_add_f32_e32 v213, v67, v213
	v_cndmask_b32_e64 v183, v183, v213, s[62:63]
	v_add_f32_e32 v214, v71, v214
	v_cndmask_b32_e64 v181, v181, v214, s[64:65]
	v_mov_b32_e32 v180, 0xf149f2ca
	v_mov_b32_e32 v182, 0xf149f2ca
	v_add_f32_e32 v215, v75, v215
	v_cndmask_b32_e64 v182, v182, v215, s[66:67]
	v_add_f32_e32 v216, v79, v216
	v_cndmask_b32_e64 v180, v180, v216, s[68:69]
	v_mov_b32_e32 v75, 0xf149f2ca
	v_mov_b32_e32 v79, 0xf149f2ca
	v_add_f32_e32 v217, v83, v217
	v_cndmask_b32_e64 v79, v79, v217, s[70:71]
	v_add_f32_e32 v218, v87, v218
	v_cndmask_b32_e64 v75, v75, v218, s[72:73]
	v_mov_b32_e32 v63, 0xf149f2ca
	v_mov_b32_e32 v67, 0xf149f2ca
	v_add_f32_e32 v219, v91, v219
	v_cndmask_b32_e64 v67, v67, v219, s[38:39]
	v_readlane_b32 s0, v255, 8
	v_readlane_b32 s1, v255, 9
	s_and_b64 s[0:1], s[0:1], s[76:77]
	s_and_b64 s[8:9], s[0:1], s[78:79]
	v_add_f32_e32 v220, v55, v220
	v_cndmask_b32_e64 v63, v63, v220, s[8:9]
	v_max_f32_e32 v55, v77, v77
	v_max_f32_e32 v55, 0xff61b1e6, v55
	v_max3_f32 v55, v55, v183, v181
	v_max3_f32 v55, v55, v182, v180
	v_max3_f32 v55, v55, v79, v75
	v_max3_f32 v55, v55, v67, v63
	s_nop 1
	v_mov_b32_dpp v71, v55 quad_perm:[1,0,3,2] row_mask:0xf bank_mask:0xf
	v_cvt_pk_bf16_f32 v52, v52, v1
	ds_write_b16 v172, v52 offset:192
	v_cvt_pk_bf16_f32 v52, v58, v1
	ds_write_b16 v172, v52 offset:224
	s_waitcnt lgkmcnt(2)
	v_max_f32_e32 v71, v71, v71
	v_max_f32_e32 v55, v55, v71
	s_nop 1
	v_mov_b32_dpp v71, v55 quad_perm:[2,3,0,1] row_mask:0xf bank_mask:0xf
	v_cvt_pk_bf16_f32 v52, v59, v1
	v_cvt_pk_bf16_f32 v80, v80, v1
	ds_write_b16 v172, v80
	v_cvt_pk_bf16_f32 v76, v76, v1
	s_waitcnt lgkmcnt(1)
	v_max_f32_e32 v71, v71, v71
	v_max_f32_e32 v55, v55, v71
	s_nop 1
	v_mov_b32_dpp v71, v55 row_shl:4 row_mask:0xf bank_mask:0x5
	v_mov_b32_dpp v71, v55 row_shr:4 row_mask:0xf bank_mask:0xa
	ds_write_b16 v172, v76 offset:32
	v_cvt_pk_bf16_f32 v64, v64, v1
	ds_write_b16 v172, v64 offset:64
	v_cvt_pk_bf16_f32 v60, v60, v1
	ds_write_b16 v172, v60 offset:96
	v_cvt_pk_bf16_f32 v57, v57, v1
	ds_write_b16 v172, v57 offset:128
	v_cvt_pk_bf16_f32 v56, v56, v1
	ds_write_b16 v172, v56 offset:160
	ds_write_b16 v172, v52 offset:256
	ds_write_b16 v122, v1 offset:288
	v_cvt_pk_bf16_f32 v52, v97, v1
	ds_write_b16 v175, v52
	v_cvt_pk_bf16_f32 v52, v89, v1
	ds_write_b16 v175, v52 offset:32
	v_cvt_pk_bf16_f32 v52, v88, v1
	ds_write_b16 v175, v52 offset:64
	v_cvt_pk_bf16_f32 v52, v85, v1
	s_waitcnt lgkmcnt(10)
	v_max_f32_e32 v71, v71, v71
	ds_write_b16 v175, v52 offset:96
	v_cvt_pk_bf16_f32 v52, v65, v1
	v_max_f32_e32 v55, v55, v71
	ds_write_b16 v175, v52 offset:128
	v_cvt_pk_bf16_f32 v52, v61, v1
	s_nop 1
	v_mov_b32_dpp v71, v55 row_shl:8 row_mask:0xf bank_mask:0x3
	v_mov_b32_dpp v71, v55 row_shr:8 row_mask:0xf bank_mask:0xc
	ds_write_b16 v175, v52 offset:160
	v_cvt_pk_bf16_f32 v52, v53, v1
	ds_write_b16 v175, v52 offset:192
	v_cvt_pk_bf16_f32 v52, v81, v1
	ds_write_b16 v175, v52 offset:224
	v_cvt_pk_bf16_f32 v52, v84, v1
	ds_write_b16 v175, v52 offset:256
	ds_write_b16 v123, v1 offset:288
	v_cvt_pk_bf16_f32 v52, v179, v1
	ds_write_b16 v175, v52 offset:336
	v_cvt_pk_bf16_f32 v52, v178, v1
	s_waitcnt lgkmcnt(6)
	v_max_f32_e32 v71, v71, v71
	ds_write_b16 v175, v52 offset:368
	v_cvt_pk_bf16_f32 v52, v90, v1
	v_max_f32_e32 v71, v55, v71
	ds_write_b16 v175, v52 offset:400
	v_cvt_pk_bf16_f32 v52, v86, v1
	v_sub_f32_e32 v55, v77, v71
	ds_write_b16 v175, v52 offset:432
	v_cvt_pk_bf16_f32 v52, v66, v1
	v_mul_f32_e32 v55, 0x3fb8aa3b, v55
	v_sub_f32_e32 v83, v183, v71
	ds_write_b16 v175, v52 offset:464
	v_cvt_pk_bf16_f32 v52, v62, v1
	v_exp_f32_e32 v55, v55
	v_mul_f32_e32 v83, 0x3fb8aa3b, v83
	v_sub_f32_e32 v87, v181, v71
	ds_write_b16 v175, v52 offset:496
	v_cvt_pk_bf16_f32 v52, v54, v1
	v_exp_f32_e32 v83, v83
	v_mul_f32_e32 v87, 0x3fb8aa3b, v87
	v_sub_f32_e32 v91, v182, v71
	ds_write_b16 v175, v52 offset:528
	v_cvt_pk_bf16_f32 v52, v78, v1
	v_add_f32_e32 v74, v176, v177
	v_exp_f32_e32 v87, v87
	v_mul_f32_e32 v91, 0x3fb8aa3b, v91
	v_sub_f32_e32 v176, v180, v71
	ds_write_b16 v175, v52 offset:560
	v_cvt_pk_bf16_f32 v52, v82, v1
	v_exp_f32_e32 v91, v91
	v_mul_f32_e32 v176, 0x3fb8aa3b, v176
	v_sub_f32_e32 v79, v79, v71
	ds_write_b16 v175, v52 offset:592
	ds_write_b16 v124, v1 offset:288
	v_cvt_pk_bf16_f32 v52, v55, v1
	v_add_f32_e32 v77, 0, v55
	v_exp_f32_e32 v176, v176
	v_mul_f32_e32 v79, 0x3fb8aa3b, v79
	v_sub_f32_e32 v75, v75, v71
	ds_write_b16 v175, v52 offset:672
	v_cvt_pk_bf16_f32 v52, v83, v1
	v_add_f32_e32 v77, v83, v77
	v_exp_f32_e32 v79, v79
	v_mul_f32_e32 v75, 0x3fb8aa3b, v75
	v_sub_f32_e32 v67, v67, v71
	ds_write_b16 v175, v52 offset:704
	v_cvt_pk_bf16_f32 v52, v87, v1
	v_add_f32_e32 v77, v87, v77
	v_exp_f32_e32 v177, v75
	v_mul_f32_e32 v67, 0x3fb8aa3b, v67
	v_sub_f32_e32 v63, v63, v71
	ds_write_b16 v175, v52 offset:736
	v_cvt_pk_bf16_f32 v52, v91, v1
	v_add_f32_e32 v77, v91, v77
	v_exp_f32_e32 v67, v67
	v_mul_f32_e32 v63, 0x3fb8aa3b, v63
	ds_write_b16 v175, v52 offset:768
	v_cvt_pk_bf16_f32 v52, v176, v1
	v_add_f32_e32 v77, v176, v77
	v_exp_f32_e32 v63, v63
	ds_write_b16 v175, v52 offset:800
	v_cvt_pk_bf16_f32 v52, v79, v1
	v_add_f32_e32 v77, v79, v77
	ds_write_b16 v175, v52 offset:832
	v_cvt_pk_bf16_f32 v52, v177, v1
	v_add_f32_e32 v75, v177, v77
	ds_write_b16 v175, v52 offset:864
	v_cvt_pk_bf16_f32 v52, v67, v1
	v_add_f32_e32 v75, v67, v75
	ds_write_b16 v175, v52 offset:896
	v_cvt_pk_bf16_f32 v52, v63, v1
	v_add_f32_e32 v75, v63, v75
	ds_write_b16 v175, v52 offset:928
	ds_write_b16 v125, v1 offset:288
	s_waitcnt lgkmcnt(0)
	s_barrier
; __device__ __forceinline__ bf16_t f2bf(float f) { return (bf16_t)(cvt_pk_bf16(f, 0.f) & 0xffffu); }
; __device__ void attn_items(const Params& p, unsigned char* shm) {
;     ...
;         f32x4 o[4];
; #pragma unroll
;         for (int nt = 0; nt < 4; ++nt) o[nt] = (f32x4){0.f, 0.f, 0.f, 0.f};
; #pragma unroll
;         for (int ks = 0; ks < 5; ++ks) { const bf16x8 ap = *(const bf16x8*)(Pw + fr * 168 + ks * 32 + fq * 8);
; #pragma unroll
;             for (int nt = 0; nt < 4; ++nt) { const int dim = nt * 16 + fr; o[nt] = __builtin_amdgcn_mfma_f32_16x16x32_bf16(ap, *(const bf16x8*)(Vt + dim * 320 + ((16 * w + ks * 32 + fq * 8) ^ ((dim >> 3) << 3))), o[nt], 0, 0, 0); } }
;         __syncthreads();
; #pragma unroll
;         for (int i = 0; i < 4; ++i) { const float inv = 1.0f / ls[i];
; #pragma unroll
;             for (int nt = 0; nt < 4; ++nt) Pw[(fq * 4 + i) * 168 + nt * 16 + fr] = f2bf(o[nt][i] * inv);
;             if (fr == 0) LSE[(size_t)(G.seq_start + G.r + G.dil * (G.q0 + 16 * w + fq * 4 + i)) * 24 + G.hd] = mx[i] + __logf(ls[i]); }
	ds_read_b128 v[52:55], v107
	ds_read_b128 v[56:59], v126 offset:36864
	ds_read_b128 v[60:63], v128 offset:36864
	ds_read_b128 v[64:67], v131 offset:36864
	ds_read_b128 v[78:81], v133 offset:36864
	s_waitcnt lgkmcnt(3)
	v_mfma_f32_16x16x32_bf16 v[56:59], v[52:55], v[56:59], 0
	s_mul_i32 s0, s58, 0xffffa000
	s_add_i32 s7, s2, s0
	s_and_b64 s[0:1], s[60:61], exec
	s_waitcnt lgkmcnt(2)
	v_mfma_f32_16x16x32_bf16 v[60:63], v[52:55], v[60:63], 0
	s_cselect_b32 s0, 4, 7
	s_sub_i32 s8, s0, s4
	s_and_b32 s7, s7, 0xfffff800
	s_waitcnt lgkmcnt(1)
	v_mfma_f32_16x16x32_bf16 v[64:67], v[52:55], v[64:67], 0
	s_and_b64 s[0:1], s[60:61], exec
	s_cselect_b32 s0, s7, 0x2000
	s_lshr_b32 s1, s6, s8
	s_waitcnt lgkmcnt(0)
	v_mfma_f32_16x16x32_bf16 v[52:55], v[52:55], v[78:81], 0
	ds_read_b128 v[78:81], v107 offset:64
	ds_read_b128 v[82:85], v134 offset:36864
	s_nop 1
	v_mov_b32_dpp v77, v75 quad_perm:[1,0,3,2] row_mask:0xf bank_mask:0xf
	s_ashr_i32 s59, s58, 31
	s_waitcnt lgkmcnt(0)
	v_mfma_f32_16x16x32_bf16 v[56:59], v[78:81], v[82:85], v[56:59]
	ds_read_b128 v[82:85], v135 offset:36864
	s_add_i32 s6, s1, s0
	s_lshl_b64 s[0:1], s[58:59], 2
	s_waitcnt lgkmcnt(0)
	v_mfma_f32_16x16x32_bf16 v[60:63], v[78:81], v[82:85], v[60:63]
	ds_read_b128 v[82:85], v136 offset:36864
	s_mov_b64 s[8:9], s[88:89]
	s_add_u32 s38, s8, s0
	s_waitcnt lgkmcnt(0)
	v_mfma_f32_16x16x32_bf16 v[64:67], v[78:81], v[82:85], v[64:67]
	ds_read_b128 v[82:85], v137 offset:36864
	s_addc_u32 s39, s9, s1
	v_add_f32_e32 v75, v75, v77
	s_waitcnt lgkmcnt(0)
	v_mfma_f32_16x16x32_bf16 v[52:55], v[78:81], v[82:85], v[52:55]
	ds_read_b128 v[78:81], v107 offset:128
	ds_read_b128 v[82:85], v138 offset:36864
	s_nop 1
	v_mov_b32_dpp v77, v75 quad_perm:[2,3,0,1] row_mask:0xf bank_mask:0xf
	v_add_u32_e32 v76, s5, v108
	s_waitcnt lgkmcnt(0)
	v_mfma_f32_16x16x32_bf16 v[56:59], v[78:81], v[82:85], v[56:59]
	ds_read_b128 v[82:85], v139 offset:36864
	s_waitcnt lgkmcnt(1)
	v_add_f32_e32 v75, v75, v77
	s_nop 1
	v_mov_b32_dpp v77, v75 row_shl:4 row_mask:0xf bank_mask:0x5
	v_mov_b32_dpp v77, v75 row_shr:4 row_mask:0xf bank_mask:0xa
	s_waitcnt lgkmcnt(0)
	v_mfma_f32_16x16x32_bf16 v[60:63], v[78:81], v[82:85], v[60:63]
	ds_read_b128 v[82:85], v140 offset:36864
	s_waitcnt lgkmcnt(1)
	v_add_f32_e32 v75, v75, v77
	s_nop 1
	v_mov_b32_dpp v77, v75 row_shl:8 row_mask:0xf bank_mask:0x3
	v_mov_b32_dpp v77, v75 row_shr:8 row_mask:0xf bank_mask:0xc
	s_waitcnt lgkmcnt(0)
	v_mfma_f32_16x16x32_bf16 v[64:67], v[78:81], v[82:85], v[64:67]
	ds_read_b128 v[82:85], v141 offset:36864
	s_waitcnt lgkmcnt(0)
	v_mfma_f32_16x16x32_bf16 v[78:81], v[78:81], v[82:85], v[52:55]
	ds_read_b128 v[82:85], v107 offset:192
	s_nop 1
	ds_read_b128 v[52:55], v142 offset:36864
	s_waitcnt lgkmcnt(0)
	v_mfma_f32_16x16x32_bf16 v[52:55], v[82:85], v[52:55], v[56:59]
	s_nop 2
	ds_read_b128 v[56:59], v143 offset:36864
	s_waitcnt lgkmcnt(0)
	v_mfma_f32_16x16x32_bf16 v[56:59], v[82:85], v[56:59], v[60:63]
	s_nop 2
	ds_read_b128 v[60:63], v144 offset:36864
	s_waitcnt lgkmcnt(0)
	v_mfma_f32_16x16x32_bf16 v[60:63], v[82:85], v[60:63], v[64:67]
	s_nop 2
	ds_read_b128 v[64:67], v145 offset:36864
	s_waitcnt lgkmcnt(0)
	v_mfma_f32_16x16x32_bf16 v[64:67], v[82:85], v[64:67], v[78:81]
	s_nop 2
	ds_read_b128 v[78:81], v107 offset:256
	ds_read_b128 v[82:85], v130 offset:36864
	s_waitcnt lgkmcnt(0)
	v_mfma_f32_16x16x32_bf16 v[52:55], v[78:81], v[82:85], v[52:55]
	ds_read_b128 v[82:85], v146 offset:36864
	s_waitcnt lgkmcnt(0)
	v_mfma_f32_16x16x32_bf16 v[56:59], v[78:81], v[82:85], v[56:59]
	ds_read_b128 v[82:85], v147 offset:36864
	s_waitcnt lgkmcnt(0)
	v_mfma_f32_16x16x32_bf16 v[60:63], v[78:81], v[82:85], v[60:63]
	ds_read_b128 v[82:85], v148 offset:36864
	s_waitcnt lgkmcnt(0)
	s_barrier
	v_mfma_f32_16x16x32_bf16 v[64:67], v[78:81], v[82:85], v[64:67]
	v_div_scale_f32 v78, s[0:1], v74, v74, 1.0
	v_rcp_f32_e32 v79, v78
	s_nop 0
	v_fma_f32 v80, -v78, v79, 1.0
	v_fmac_f32_e32 v79, v80, v79
	v_div_scale_f32 v80, vcc, 1.0, v74, 1.0
	v_mul_f32_e32 v81, v80, v79
	v_fma_f32 v82, -v78, v81, v80
	v_fmac_f32_e32 v81, v82, v79
	v_fma_f32 v78, -v78, v81, v80
	v_div_fmas_f32 v78, v78, v79, v81
	v_div_fixup_f32 v78, v78, v74, 1.0
	v_mul_f32_e32 v52, v78, v52
	v_cvt_pk_bf16_f32 v52, v52, v1
	ds_write_b16 v172, v52
	v_mul_f32_e32 v52, v78, v56
	v_cvt_pk_bf16_f32 v52, v52, v1
	ds_write_b16 v172, v52 offset:32
	v_mul_f32_e32 v52, v78, v60
	v_cvt_pk_bf16_f32 v52, v52, v1
	ds_write_b16 v172, v52 offset:64
	v_mul_f32_e32 v52, v78, v64
	v_cvt_pk_bf16_f32 v52, v52, v1
	ds_write_b16 v172, v52 offset:96
	s_and_saveexec_b64 s[0:1], s[36:37]
	s_cbranch_execz .LBB0_447
	s_mov_b32 s5, 0x800000
	v_cmp_gt_f32_e32 vcc, s5, v74
	s_mov_b32 s5, 0x3f317217
	v_mov_b64_e32 v[78:79], s[38:39]
	v_cndmask_b32_e64 v52, 0, 32, vcc
	v_ldexp_f32 v52, v74, v52
	v_log_f32_e32 v52, v52
	v_cndmask_b32_e32 v56, 0, v231, vcc
	v_mul_f32_e32 v60, 0x3f317217, v52
	v_fma_f32 v60, v52, s5, -v60
	v_fmac_f32_e32 v60, 0x3377d1cf, v52
	s_mov_b32 s5, 0x7f800000
	v_fmac_f32_e32 v60, 0x3f317217, v52
	v_cmp_lt_f32_e64 vcc, |v52|, s5
	s_nop 1
	v_cndmask_b32_e32 v52, v52, v60, vcc
	v_sub_f32_e32 v52, v52, v56
	v_add_f32_e32 v2, v2, v52
	v_lshlrev_b32_e32 v52, s4, v76
	v_add_u32_e32 v52, s6, v52
	v_mad_i64_i32 v[78:79], s[8:9], v52, s82, v[78:79]
	global_store_dword v[78:79], v2, off
